# v093 + the last 3840 items of the layer-1 in/out projection weights also converted in the down-L0 idle tail instead of P0
# baseline (speedup 1.0000x reference)
; #define LAS __attribute__((address_space(3)))
; __device__ __forceinline__ void p0_weights(KAP a, LAS unsigned char* lds, int gw, int NGW, int wave, int lane) {
;     LAS float* scr = (LAS float*)(lds + wave * 8704);
;     unsigned char* ws = a->ws;
;     constexpr int I_TOTAL = (2048 / 64) * (2624 / 32) + (512 / 64) * (1536 / 32) + (512 / 64) * (2048 / 32) + 2 * (2048 / 64) * (2048 / 32) + (2048 / 64) * (4608 / 32)
;                           + 4 * (2048 / 64) * (DFF / 32) + 2 * (DFF / 64) * (2048 / 32);
;     for (int item = gw; item < I_TOTAL; item += NGW) {
;         int it = item;
;         if (conv_matrix(it, a->in[13], 2048, 2624, (bf16*)(ws + WS_WIN0), 0, scr, lane)) continue;
.LBB0_36:
	v_mbcnt_lo_u32_b32 v2, -1, 0
	v_mbcnt_hi_u32_b32 v2, -1, v2
	s_lshl_b32 s5, s87, 3
	v_add_u32_e32 v0, s93, v2
	s_lshl_b32 s33, s74, 3
	v_readfirstlane_b32 s4, v0
	s_ashr_i32 s6, s4, 6
	s_add_i32 s99, s6, s5
	v_writelane_b32 v253, s87, 2
	s_mov_b64 s[4:5], s[0:1]
	s_cmp_gt_i32 s99, 0x62bf
	s_cbranch_scc1 .LBB0_119
	s_load_dwordx2 s[8:9], s[4:5], 0xf0
	v_bfe_u32 v0, v2, 5, 1
	v_and_b32_e32 v28, 31, v2
	v_bfe_u32 v1, v2, 3, 3
	v_lshlrev_b32_e32 v2, 3, v2
	v_and_b32_e32 v2, 56, v2
	v_mov_b32_e32 v3, 0
	v_mul_u32_u24_e32 v6, 0x84, v2
	v_lshlrev_b32_e32 v2, 1, v2
	s_mul_i32 s10, s6, 0x2200
	s_waitcnt lgkmcnt(0)
	v_lshl_add_u64 v[22:23], s[8:9], 0, v[2:3]
	s_mov_b64 s[6:7], 0x100000
	s_add_i32 s11, s10, 0
	v_lshl_add_u64 v[4:5], v[22:23], 0, s[6:7]
	v_lshlrev_b32_e32 v2, 2, v1
	s_mov_b64 s[6:7], 0xc00000
	v_add3_u32 v44, s11, v6, v2
	v_lshl_add_u64 v[6:7], v[22:23], 0, s[6:7]
	s_mov_b64 s[6:7], 0xe00000
	v_lshl_add_u64 v[8:9], v[22:23], 0, s[6:7]
	s_mov_b64 s[6:7], 0x1000000
	v_lshl_add_u64 v[10:11], v[22:23], 0, s[6:7]
	s_mov_b64 s[6:7], 0x1800000
	v_lshl_add_u64 v[12:13], v[22:23], 0, s[6:7]
	s_mov_b64 s[6:7], 0x2a00000
	v_lshl_add_u64 v[14:15], v[22:23], 0, s[6:7]
	s_mov_b64 s[6:7], 0x3200000
	v_lshl_add_u64 v[16:17], v[22:23], 0, s[6:7]
	s_mov_b64 s[6:7], 0x5e00000
	v_lshl_add_u64 v[18:19], v[22:23], 0, s[6:7]
	s_mov_b64 s[6:7], 0x8a00000
	v_mul_u32_u24_e32 v2, 0x84, v0
	v_lshl_add_u64 v[20:21], v[22:23], 0, s[6:7]
	s_mov_b64 s[6:7], 0xa000000
	v_or_b32_e32 v2, s10, v2
	v_lshlrev_b32_e32 v24, 2, v28
	v_or_b32_e32 v45, 8, v1
	v_or_b32_e32 v46, 16, v1
	v_or_b32_e32 v47, 24, v1
	v_lshl_add_u64 v[22:23], v[22:23], 0, s[6:7]
	v_add3_u32 v48, v2, v24, 0
	v_mov_b32_e32 v25, v3
	v_or_b32_e32 v49, 14, v0
	v_or_b32_e32 v50, 12, v0
	v_or_b32_e32 v51, 10, v0
	v_or_b32_e32 v52, 8, v0
	v_or_b32_e32 v53, 6, v0
	v_or_b32_e32 v54, 4, v0
	v_or_b32_e32 v55, 2, v0
	v_or_b32_e32 v26, 0x2c00000, v24
	v_mov_b32_e32 v27, v3
	s_movk_i32 s23, 0x2900
	s_movk_i32 s24, 0x7fff
	s_mov_b32 s25, 0xffff0000
	s_movk_i32 s26, 0x1800
	s_movk_i32 s27, 0x4800
	s_movk_i32 s28, 0x1600
	s_movk_i32 s29, 0x5800
	s_mov_b64 s[6:7], 0x2c00000
	v_lshlrev_b32_e32 v2, 2, v28
	v_mov_b32_e32 v56, 0x4800
	v_mov_b32_e32 v57, 0x5800
	s_branch .LBB0_39
